# UV GEMM EpiColT<4> epilogue rewritten too (all 16 statistics loads in flight; accumulator map taken from the compiler's code)
# baseline (speedup 1.0000x reference)
.LBB0_891:
	v_mov_b32_e32 v134, v206
	s_lshl_b32 s13, s45, 8
	s_add_i32 s13, s13, s40
	v_and_or_b32 v140, v134, 15, s13
	s_lshl_b32 s13, s44, 8
	v_lshrrev_b32_e32 v134, 1, v134
	v_and_or_b32 v134, v134, 24, s13
	v_or_b32_e32 v134, s41, v134
	v_mov_b32_e32 v146, v134
	v_mov_b32_e32 v147, v140
	v_lshlrev_b32_e32 v150, 4, v146
	v_add_u32_e32 v151, 0x800, v150
	global_load_dwordx4 v[164:167], v150, s[4:5] offset:0
	global_load_dwordx4 v[168:171], v150, s[4:5] offset:16
	global_load_dwordx4 v[172:175], v150, s[4:5] offset:32
	global_load_dwordx4 v[176:179], v150, s[4:5] offset:48
	global_load_dwordx4 v[180:183], v150, s[4:5] offset:64
	global_load_dwordx4 v[184:187], v150, s[4:5] offset:80
	global_load_dwordx4 v[188:191], v150, s[4:5] offset:96
	global_load_dwordx4 v[192:195], v150, s[4:5] offset:112
	global_load_dwordx4 v[196:199], v151, s[4:5] offset:0
	global_load_dwordx4 v[200:203], v151, s[4:5] offset:16
	global_load_dwordx4 v[218:221], v151, s[4:5] offset:32
	global_load_dwordx4 v[222:225], v151, s[4:5] offset:48
	global_load_dwordx4 v[226:229], v151, s[4:5] offset:64
	global_load_dwordx4 v[230:233], v151, s[4:5] offset:80
	global_load_dwordx4 v[212:215], v151, s[4:5] offset:96
	global_load_dwordx4 v[154:157], v151, s[4:5] offset:112
	s_waitcnt vmcnt(15)
	v_add_f32_e32 v164, v164, v165
	v_add_f32_e32 v166, v166, v167
	v_add_f32_e32 v164, v164, v166
	v_fmamk_f32 v164, v164, 0x3b800000, v207
	v_rsq_f32_e32 v152, v164
	s_waitcnt vmcnt(14)
	v_add_f32_e32 v168, v168, v169
	v_add_f32_e32 v170, v170, v171
	v_add_f32_e32 v168, v168, v170
	v_fmamk_f32 v168, v168, 0x3b800000, v207
	v_rsq_f32_e32 v153, v168
	s_waitcnt vmcnt(13)
	v_add_f32_e32 v172, v172, v173
	v_add_f32_e32 v174, v174, v175
	v_add_f32_e32 v172, v172, v174
	v_fmamk_f32 v172, v172, 0x3b800000, v207
	v_rsq_f32_e32 v162, v172
	s_waitcnt vmcnt(12)
	v_add_f32_e32 v176, v176, v177
	v_add_f32_e32 v178, v178, v179
	v_add_f32_e32 v176, v176, v178
	v_fmamk_f32 v176, v176, 0x3b800000, v207
	v_rsq_f32_e32 v163, v176
	s_waitcnt vmcnt(11)
	v_add_f32_e32 v180, v180, v181
	v_add_f32_e32 v182, v182, v183
	v_add_f32_e32 v180, v180, v182
	v_fmamk_f32 v180, v180, 0x3b800000, v207
	v_rsq_f32_e32 v204, v180
	s_waitcnt vmcnt(10)
	v_add_f32_e32 v184, v184, v185
	v_add_f32_e32 v186, v186, v187
	v_add_f32_e32 v184, v184, v186
	v_fmamk_f32 v184, v184, 0x3b800000, v207
	v_rsq_f32_e32 v205, v184
	s_waitcnt vmcnt(9)
	v_add_f32_e32 v188, v188, v189
	v_add_f32_e32 v190, v190, v191
	v_add_f32_e32 v188, v188, v190
	v_fmamk_f32 v188, v188, 0x3b800000, v207
	v_rsq_f32_e32 v208, v188
	s_waitcnt vmcnt(8)
	v_add_f32_e32 v192, v192, v193
	v_add_f32_e32 v194, v194, v195
	v_add_f32_e32 v192, v192, v194
	v_fmamk_f32 v192, v192, 0x3b800000, v207
	v_rsq_f32_e32 v209, v192
	s_waitcnt vmcnt(7)
	v_add_f32_e32 v196, v196, v197
	v_add_f32_e32 v198, v198, v199
	v_add_f32_e32 v196, v196, v198
	v_fmamk_f32 v196, v196, 0x3b800000, v207
	v_rsq_f32_e32 v248, v196
	s_waitcnt vmcnt(6)
	v_add_f32_e32 v200, v200, v201
	v_add_f32_e32 v202, v202, v203
	v_add_f32_e32 v200, v200, v202
	v_fmamk_f32 v200, v200, 0x3b800000, v207
	v_rsq_f32_e32 v249, v200
	s_waitcnt vmcnt(5)
	v_add_f32_e32 v218, v218, v219
	v_add_f32_e32 v220, v220, v221
	v_add_f32_e32 v218, v218, v220
	v_fmamk_f32 v218, v218, 0x3b800000, v207
	v_rsq_f32_e32 v136, v218
	s_waitcnt vmcnt(4)
	v_add_f32_e32 v222, v222, v223
	v_add_f32_e32 v224, v224, v225
	v_add_f32_e32 v222, v222, v224
	v_fmamk_f32 v222, v222, 0x3b800000, v207
	v_rsq_f32_e32 v137, v222
	s_waitcnt vmcnt(3)
	v_add_f32_e32 v226, v226, v227
	v_add_f32_e32 v228, v228, v229
	v_add_f32_e32 v226, v226, v228
	v_fmamk_f32 v226, v226, 0x3b800000, v207
	v_rsq_f32_e32 v138, v226
	s_waitcnt vmcnt(2)
	v_add_f32_e32 v230, v230, v231
	v_add_f32_e32 v232, v232, v233
	v_add_f32_e32 v230, v230, v232
	v_fmamk_f32 v230, v230, 0x3b800000, v207
	v_rsq_f32_e32 v139, v230
	s_waitcnt vmcnt(1)
	v_add_f32_e32 v212, v212, v213
	v_add_f32_e32 v214, v214, v215
	v_add_f32_e32 v212, v212, v214
	v_fmamk_f32 v212, v212, 0x3b800000, v207
	v_rsq_f32_e32 v144, v212
	s_waitcnt vmcnt(0)
	v_add_f32_e32 v154, v154, v155
	v_add_f32_e32 v156, v156, v157
	v_add_f32_e32 v154, v154, v156
	v_fmamk_f32 v154, v154, 0x3b800000, v207
	v_rsq_f32_e32 v145, v154
	v_lshlrev_b32_e32 v164, 16, v147
	v_lshl_add_u32 v164, v146, 1, v164
	v_add_u32_e32 v165, 0x100000, v164
	v_add_u32_e32 v166, 0x200000, v164
	v_add_u32_e32 v167, 0x300000, v164
	v_add_u32_e32 v168, 0x800000, v164
	v_add_u32_e32 v169, 0x900000, v164
	v_add_u32_e32 v170, 0xa00000, v164
	v_add_u32_e32 v171, 0xb00000, v164
	v_pk_mul_f32 v[124:125], v[124:125], v[152:153]
	v_pk_mul_f32 v[126:127], v[126:127], v[162:163]
	v_cvt_pk_bf16_f32 v172, v124, v125
	v_cvt_pk_bf16_f32 v173, v126, v127
	global_store_dwordx2 v164, v[172:173], s[2:3]
	v_pk_mul_f32 v[120:121], v[120:121], v[152:153]
	v_pk_mul_f32 v[122:123], v[122:123], v[162:163]
	v_cvt_pk_bf16_f32 v174, v120, v121
	v_cvt_pk_bf16_f32 v175, v122, v123
	global_store_dwordx2 v165, v[174:175], s[2:3]
	v_pk_mul_f32 v[116:117], v[116:117], v[152:153]
	v_pk_mul_f32 v[118:119], v[118:119], v[162:163]
	v_cvt_pk_bf16_f32 v176, v116, v117
	v_cvt_pk_bf16_f32 v177, v118, v119
	global_store_dwordx2 v166, v[176:177], s[2:3]
	v_pk_mul_f32 v[112:113], v[112:113], v[152:153]
	v_pk_mul_f32 v[114:115], v[114:115], v[162:163]
	v_cvt_pk_bf16_f32 v178, v112, v113
	v_cvt_pk_bf16_f32 v179, v114, v115
	global_store_dwordx2 v167, v[178:179], s[2:3]
	v_pk_mul_f32 v[108:109], v[108:109], v[152:153]
	v_pk_mul_f32 v[110:111], v[110:111], v[162:163]
	v_cvt_pk_bf16_f32 v172, v108, v109
	v_cvt_pk_bf16_f32 v173, v110, v111
	global_store_dwordx2 v168, v[172:173], s[2:3]
	v_pk_mul_f32 v[104:105], v[104:105], v[152:153]
	v_pk_mul_f32 v[106:107], v[106:107], v[162:163]
	v_cvt_pk_bf16_f32 v174, v104, v105
	v_cvt_pk_bf16_f32 v175, v106, v107
	global_store_dwordx2 v169, v[174:175], s[2:3]
	v_pk_mul_f32 v[100:101], v[100:101], v[152:153]
	v_pk_mul_f32 v[102:103], v[102:103], v[162:163]
	v_cvt_pk_bf16_f32 v176, v100, v101
	v_cvt_pk_bf16_f32 v177, v102, v103
	global_store_dwordx2 v170, v[176:177], s[2:3]
	v_pk_mul_f32 v[96:97], v[96:97], v[152:153]
	v_pk_mul_f32 v[98:99], v[98:99], v[162:163]
	v_cvt_pk_bf16_f32 v178, v96, v97
	v_cvt_pk_bf16_f32 v179, v98, v99
	global_store_dwordx2 v171, v[178:179], s[2:3]
	v_pk_mul_f32 v[92:93], v[92:93], v[204:205]
	v_pk_mul_f32 v[94:95], v[94:95], v[208:209]
	v_cvt_pk_bf16_f32 v172, v92, v93
	v_cvt_pk_bf16_f32 v173, v94, v95
	global_store_dwordx2 v164, v[172:173], s[2:3] offset:8
	v_pk_mul_f32 v[84:85], v[84:85], v[204:205]
	v_pk_mul_f32 v[86:87], v[86:87], v[208:209]
	v_cvt_pk_bf16_f32 v174, v84, v85
	v_cvt_pk_bf16_f32 v175, v86, v87
	global_store_dwordx2 v165, v[174:175], s[2:3] offset:8
	v_pk_mul_f32 v[76:77], v[76:77], v[204:205]
	v_pk_mul_f32 v[78:79], v[78:79], v[208:209]
	v_cvt_pk_bf16_f32 v176, v76, v77
	v_cvt_pk_bf16_f32 v177, v78, v79
	global_store_dwordx2 v166, v[176:177], s[2:3] offset:8
	v_pk_mul_f32 v[72:73], v[72:73], v[204:205]
	v_pk_mul_f32 v[74:75], v[74:75], v[208:209]
	v_cvt_pk_bf16_f32 v178, v72, v73
	v_cvt_pk_bf16_f32 v179, v74, v75
	global_store_dwordx2 v167, v[178:179], s[2:3] offset:8
	v_pk_mul_f32 v[88:89], v[88:89], v[204:205]
	v_pk_mul_f32 v[90:91], v[90:91], v[208:209]
	v_cvt_pk_bf16_f32 v172, v88, v89
	v_cvt_pk_bf16_f32 v173, v90, v91
	global_store_dwordx2 v168, v[172:173], s[2:3] offset:8
	v_pk_mul_f32 v[80:81], v[80:81], v[204:205]
	v_pk_mul_f32 v[82:83], v[82:83], v[208:209]
	v_cvt_pk_bf16_f32 v174, v80, v81
	v_cvt_pk_bf16_f32 v175, v82, v83
	global_store_dwordx2 v169, v[174:175], s[2:3] offset:8
	v_pk_mul_f32 v[68:69], v[68:69], v[204:205]
	v_pk_mul_f32 v[70:71], v[70:71], v[208:209]
	v_cvt_pk_bf16_f32 v176, v68, v69
	v_cvt_pk_bf16_f32 v177, v70, v71
	global_store_dwordx2 v170, v[176:177], s[2:3] offset:8
	v_pk_mul_f32 v[64:65], v[64:65], v[204:205]
	v_pk_mul_f32 v[66:67], v[66:67], v[208:209]
	v_cvt_pk_bf16_f32 v178, v64, v65
	v_cvt_pk_bf16_f32 v179, v66, v67
	global_store_dwordx2 v171, v[178:179], s[2:3] offset:8
	v_pk_mul_f32 v[44:45], v[44:45], v[248:249]
	v_pk_mul_f32 v[46:47], v[46:47], v[136:137]
	v_cvt_pk_bf16_f32 v172, v44, v45
	v_cvt_pk_bf16_f32 v173, v46, v47
	global_store_dwordx2 v164, v[172:173], s[2:3] offset:256
	v_pk_mul_f32 v[40:41], v[40:41], v[248:249]
	v_pk_mul_f32 v[42:43], v[42:43], v[136:137]
	v_cvt_pk_bf16_f32 v174, v40, v41
	v_cvt_pk_bf16_f32 v175, v42, v43
	global_store_dwordx2 v165, v[174:175], s[2:3] offset:256
	v_pk_mul_f32 v[36:37], v[36:37], v[248:249]
	v_pk_mul_f32 v[38:39], v[38:39], v[136:137]
	v_cvt_pk_bf16_f32 v176, v36, v37
	v_cvt_pk_bf16_f32 v177, v38, v39
	global_store_dwordx2 v166, v[176:177], s[2:3] offset:256
	v_pk_mul_f32 v[32:33], v[32:33], v[248:249]
	v_pk_mul_f32 v[34:35], v[34:35], v[136:137]
	v_cvt_pk_bf16_f32 v178, v32, v33
	v_cvt_pk_bf16_f32 v179, v34, v35
	global_store_dwordx2 v167, v[178:179], s[2:3] offset:256
	v_pk_mul_f32 v[60:61], v[60:61], v[248:249]
	v_pk_mul_f32 v[62:63], v[62:63], v[136:137]
	v_cvt_pk_bf16_f32 v172, v60, v61
	v_cvt_pk_bf16_f32 v173, v62, v63
	global_store_dwordx2 v168, v[172:173], s[2:3] offset:256
	v_pk_mul_f32 v[56:57], v[56:57], v[248:249]
	v_pk_mul_f32 v[58:59], v[58:59], v[136:137]
	v_cvt_pk_bf16_f32 v174, v56, v57
	v_cvt_pk_bf16_f32 v175, v58, v59
	global_store_dwordx2 v169, v[174:175], s[2:3] offset:256
	v_pk_mul_f32 v[52:53], v[52:53], v[248:249]
	v_pk_mul_f32 v[54:55], v[54:55], v[136:137]
	v_cvt_pk_bf16_f32 v176, v52, v53
	v_cvt_pk_bf16_f32 v177, v54, v55
	global_store_dwordx2 v170, v[176:177], s[2:3] offset:256
	v_pk_mul_f32 v[48:49], v[48:49], v[248:249]
	v_pk_mul_f32 v[50:51], v[50:51], v[136:137]
	v_cvt_pk_bf16_f32 v178, v48, v49
	v_cvt_pk_bf16_f32 v179, v50, v51
	global_store_dwordx2 v171, v[178:179], s[2:3] offset:256
	v_pk_mul_f32 v[12:13], v[12:13], v[138:139]
	v_pk_mul_f32 v[14:15], v[14:15], v[144:145]
	v_cvt_pk_bf16_f32 v172, v12, v13
	v_cvt_pk_bf16_f32 v173, v14, v15
	global_store_dwordx2 v164, v[172:173], s[2:3] offset:264
	v_pk_mul_f32 v[8:9], v[8:9], v[138:139]
	v_pk_mul_f32 v[10:11], v[10:11], v[144:145]
	v_cvt_pk_bf16_f32 v174, v8, v9
	v_cvt_pk_bf16_f32 v175, v10, v11
	global_store_dwordx2 v165, v[174:175], s[2:3] offset:264
	v_pk_mul_f32 v[4:5], v[4:5], v[138:139]
	v_pk_mul_f32 v[6:7], v[6:7], v[144:145]
	v_cvt_pk_bf16_f32 v176, v4, v5
	v_cvt_pk_bf16_f32 v177, v6, v7
	global_store_dwordx2 v166, v[176:177], s[2:3] offset:264
	v_pk_mul_f32 v[0:1], v[0:1], v[138:139]
	v_pk_mul_f32 v[2:3], v[2:3], v[144:145]
	v_cvt_pk_bf16_f32 v178, v0, v1
	v_cvt_pk_bf16_f32 v179, v2, v3
	global_store_dwordx2 v167, v[178:179], s[2:3] offset:264
	v_pk_mul_f32 v[28:29], v[28:29], v[138:139]
	v_pk_mul_f32 v[30:31], v[30:31], v[144:145]
	v_cvt_pk_bf16_f32 v172, v28, v29
	v_cvt_pk_bf16_f32 v173, v30, v31
	global_store_dwordx2 v168, v[172:173], s[2:3] offset:264
	v_pk_mul_f32 v[24:25], v[24:25], v[138:139]
	v_pk_mul_f32 v[26:27], v[26:27], v[144:145]
	v_cvt_pk_bf16_f32 v174, v24, v25
	v_cvt_pk_bf16_f32 v175, v26, v27
	global_store_dwordx2 v169, v[174:175], s[2:3] offset:264
	v_pk_mul_f32 v[20:21], v[20:21], v[138:139]
	v_pk_mul_f32 v[22:23], v[22:23], v[144:145]
	v_cvt_pk_bf16_f32 v176, v20, v21
	v_cvt_pk_bf16_f32 v177, v22, v23
	global_store_dwordx2 v170, v[176:177], s[2:3] offset:264
	v_pk_mul_f32 v[16:17], v[16:17], v[138:139]
	v_pk_mul_f32 v[18:19], v[18:19], v[144:145]
	v_cvt_pk_bf16_f32 v178, v16, v17
	v_cvt_pk_bf16_f32 v179, v18, v19
	global_store_dwordx2 v171, v[178:179], s[2:3] offset:264
	s_mov_b32 s13, 0xb00000
	s_mov_b64 s[20:21], -1
	s_mov_b32 s49, s59
	v_mov_b64_e32 v[250:251], 0x200
	s_andn2_b64 vcc, exec, s[6:7]
	s_cbranch_vccnz .LBB0_882
	s_andn2_b64 vcc, exec, s[0:1]
	s_cbranch_vccnz .LBB0_881
	s_barrier
	s_branch .LBB0_881
